# phase 0 mod_gemv: w_mod loads issued 32 at a time (4 k-blocks ahead) instead of 8 per serialized batch
# baseline (speedup 1.0000x reference)
.LBB0_81:
	s_bitcmp1_b32 s10, 17
	s_cbranch_scc1 .Lmg_hi
	s_bitcmp1_b32 s10, 16
	s_cbranch_scc1 .Lmg_c1
	s_add_u32 s2, s10, 0x0
	s_addc_u32 s3, s11, 0
	v_lshl_add_u64 v[116:117], v[46:47], 0, s[2:3]
	global_load_dword v120, v[116:117], off
	s_add_u32 s2, s10, 0x6000
	s_addc_u32 s3, s11, 0
	v_lshl_add_u64 v[116:117], v[46:47], 0, s[2:3]
	global_load_dword v121, v[116:117], off
	s_add_u32 s2, s10, 0xc000
	s_addc_u32 s3, s11, 0
	v_lshl_add_u64 v[116:117], v[46:47], 0, s[2:3]
	global_load_dword v122, v[116:117], off
	s_add_u32 s2, s10, 0x12000
	s_addc_u32 s3, s11, 0
	v_lshl_add_u64 v[116:117], v[46:47], 0, s[2:3]
	global_load_dword v123, v[116:117], off
	s_add_u32 s2, s10, 0x18000
	s_addc_u32 s3, s11, 0
	v_lshl_add_u64 v[116:117], v[46:47], 0, s[2:3]
	global_load_dword v124, v[116:117], off
	s_add_u32 s2, s10, 0x1e000
	s_addc_u32 s3, s11, 0
	v_lshl_add_u64 v[116:117], v[46:47], 0, s[2:3]
	global_load_dword v125, v[116:117], off
	s_add_u32 s2, s10, 0x24000
	s_addc_u32 s3, s11, 0
	v_lshl_add_u64 v[116:117], v[46:47], 0, s[2:3]
	global_load_dword v126, v[116:117], off
	s_add_u32 s2, s10, 0x2a000
	s_addc_u32 s3, s11, 0
	v_lshl_add_u64 v[116:117], v[46:47], 0, s[2:3]
	global_load_dword v127, v[116:117], off
	s_add_u32 s2, s10, 0x30000
	s_addc_u32 s3, s11, 0
	v_lshl_add_u64 v[116:117], v[46:47], 0, s[2:3]
	global_load_dword v128, v[116:117], off
	s_add_u32 s2, s10, 0x36000
	s_addc_u32 s3, s11, 0
	v_lshl_add_u64 v[116:117], v[46:47], 0, s[2:3]
	global_load_dword v129, v[116:117], off
	s_add_u32 s2, s10, 0x3c000
	s_addc_u32 s3, s11, 0
	v_lshl_add_u64 v[116:117], v[46:47], 0, s[2:3]
	global_load_dword v130, v[116:117], off
	s_add_u32 s2, s10, 0x42000
	s_addc_u32 s3, s11, 0
	v_lshl_add_u64 v[116:117], v[46:47], 0, s[2:3]
	global_load_dword v131, v[116:117], off
	s_add_u32 s2, s10, 0x48000
	s_addc_u32 s3, s11, 0
	v_lshl_add_u64 v[116:117], v[46:47], 0, s[2:3]
	global_load_dword v132, v[116:117], off
	s_add_u32 s2, s10, 0x4e000
	s_addc_u32 s3, s11, 0
	v_lshl_add_u64 v[116:117], v[46:47], 0, s[2:3]
	global_load_dword v133, v[116:117], off
	s_add_u32 s2, s10, 0x54000
	s_addc_u32 s3, s11, 0
	v_lshl_add_u64 v[116:117], v[46:47], 0, s[2:3]
	global_load_dword v134, v[116:117], off
	s_add_u32 s2, s10, 0x5a000
	s_addc_u32 s3, s11, 0
	v_lshl_add_u64 v[116:117], v[46:47], 0, s[2:3]
	global_load_dword v135, v[116:117], off
	s_add_u32 s2, s10, 0x60000
	s_addc_u32 s3, s11, 0
	v_lshl_add_u64 v[116:117], v[46:47], 0, s[2:3]
	global_load_dword v136, v[116:117], off
	s_add_u32 s2, s10, 0x66000
	s_addc_u32 s3, s11, 0
	v_lshl_add_u64 v[116:117], v[46:47], 0, s[2:3]
	global_load_dword v137, v[116:117], off
	s_add_u32 s2, s10, 0x6c000
	s_addc_u32 s3, s11, 0
	v_lshl_add_u64 v[116:117], v[46:47], 0, s[2:3]
	global_load_dword v138, v[116:117], off
	s_add_u32 s2, s10, 0x72000
	s_addc_u32 s3, s11, 0
	v_lshl_add_u64 v[116:117], v[46:47], 0, s[2:3]
	global_load_dword v139, v[116:117], off
	s_add_u32 s2, s10, 0x78000
	s_addc_u32 s3, s11, 0
	v_lshl_add_u64 v[116:117], v[46:47], 0, s[2:3]
	global_load_dword v140, v[116:117], off
	s_add_u32 s2, s10, 0x7e000
	s_addc_u32 s3, s11, 0
	v_lshl_add_u64 v[116:117], v[46:47], 0, s[2:3]
	global_load_dword v141, v[116:117], off
	s_add_u32 s2, s10, 0x84000
	s_addc_u32 s3, s11, 0
	v_lshl_add_u64 v[116:117], v[46:47], 0, s[2:3]
	global_load_dword v142, v[116:117], off
	s_add_u32 s2, s10, 0x8a000
	s_addc_u32 s3, s11, 0
	v_lshl_add_u64 v[116:117], v[46:47], 0, s[2:3]
	global_load_dword v143, v[116:117], off
	s_add_u32 s2, s10, 0x90000
	s_addc_u32 s3, s11, 0
	v_lshl_add_u64 v[116:117], v[46:47], 0, s[2:3]
	global_load_dword v144, v[116:117], off
	s_add_u32 s2, s10, 0x96000
	s_addc_u32 s3, s11, 0
	v_lshl_add_u64 v[116:117], v[46:47], 0, s[2:3]
	global_load_dword v145, v[116:117], off
	s_add_u32 s2, s10, 0x9c000
	s_addc_u32 s3, s11, 0
	v_lshl_add_u64 v[116:117], v[46:47], 0, s[2:3]
	global_load_dword v146, v[116:117], off
	s_add_u32 s2, s10, 0xa2000
	s_addc_u32 s3, s11, 0
	v_lshl_add_u64 v[116:117], v[46:47], 0, s[2:3]
	global_load_dword v147, v[116:117], off
	s_add_u32 s2, s10, 0xa8000
	s_addc_u32 s3, s11, 0
	v_lshl_add_u64 v[116:117], v[46:47], 0, s[2:3]
	global_load_dword v148, v[116:117], off
	s_add_u32 s2, s10, 0xae000
	s_addc_u32 s3, s11, 0
	v_lshl_add_u64 v[116:117], v[46:47], 0, s[2:3]
	global_load_dword v149, v[116:117], off
	s_add_u32 s2, s10, 0xb4000
	s_addc_u32 s3, s11, 0
	v_lshl_add_u64 v[116:117], v[46:47], 0, s[2:3]
	global_load_dword v150, v[116:117], off
	s_add_u32 s2, s10, 0xba000
	s_addc_u32 s3, s11, 0
	v_lshl_add_u64 v[116:117], v[46:47], 0, s[2:3]
	global_load_dword v151, v[116:117], off
	s_waitcnt vmcnt(24)
	v_mov_b32_e32 v112, v120
	v_mov_b32_e32 v100, v121
	v_mov_b32_e32 v102, v122
	v_mov_b32_e32 v104, v123
	v_mov_b32_e32 v106, v124
	v_mov_b32_e32 v108, v125
	v_mov_b32_e32 v110, v126
	v_mov_b32_e32 v98, v127
	s_branch .Lmg_go
.Lmg_c1:
	s_waitcnt vmcnt(0)
	v_mov_b32_e32 v112, v144
	v_mov_b32_e32 v100, v145
	v_mov_b32_e32 v102, v146
	v_mov_b32_e32 v104, v147
	v_mov_b32_e32 v106, v148
	v_mov_b32_e32 v108, v149
	v_mov_b32_e32 v110, v150
	v_mov_b32_e32 v98, v151
	s_branch .Lmg_go
.Lmg_hi:
	s_bitcmp1_b32 s10, 16
	s_cbranch_scc1 .Lmg_c3
	s_waitcnt vmcnt(8)
	v_mov_b32_e32 v112, v136
	v_mov_b32_e32 v100, v137
	v_mov_b32_e32 v102, v138
	v_mov_b32_e32 v104, v139
	v_mov_b32_e32 v106, v140
	v_mov_b32_e32 v108, v141
	v_mov_b32_e32 v110, v142
	v_mov_b32_e32 v98, v143
	s_branch .Lmg_go
.Lmg_c3:
	s_waitcnt vmcnt(16)
	v_mov_b32_e32 v112, v128
	v_mov_b32_e32 v100, v129
	v_mov_b32_e32 v102, v130
	v_mov_b32_e32 v104, v131
	v_mov_b32_e32 v106, v132
	v_mov_b32_e32 v108, v133
	v_mov_b32_e32 v110, v134
	v_mov_b32_e32 v98, v135
.Lmg_go:
	ds_read_b128 v[8:11], v60
	ds_read_b128 v[0:3], v60 offset:16
	ds_read_b128 v[4:7], v60 offset:4096
	ds_read_b128 v[12:15], v60 offset:4112
	ds_read_b128 v[62:65], v60 offset:8192
	ds_read_b128 v[66:69], v60 offset:8208
	ds_read_b128 v[24:27], v60 offset:12288
	ds_read_b128 v[16:19], v60 offset:12304
	ds_read_b128 v[70:73], v60 offset:16384
	ds_read_b128 v[74:77], v60 offset:16400
	ds_read_b128 v[28:31], v60 offset:20480
	ds_read_b128 v[20:23], v60 offset:20496
	ds_read_b128 v[78:81], v60 offset:24576
	ds_read_b128 v[82:85], v60 offset:24592
	ds_read_b128 v[86:89], v60 offset:28672
	ds_read_b128 v[32:35], v60 offset:28688
	ds_read_b128 v[90:93], v60 offset:32768
	ds_read_b128 v[94:97], v60 offset:32784
	s_nop 0
	s_waitcnt lgkmcnt(14)
	v_mov_b32_e32 v114, v8
	v_mov_b32_e32 v115, v4
	s_nop 0
	v_mov_b32_e32 v4, v9
	s_nop 0
	v_mov_b32_e32 v8, v10
	s_nop 0
	v_mov_b32_e32 v9, v6
	v_mov_b32_e32 v6, v11
	s_waitcnt lgkmcnt(13)
	v_mov_b32_e32 v10, v62
	s_waitcnt lgkmcnt(11)
	v_mov_b32_e32 v11, v24
	v_mov_b32_e32 v24, v63
	v_mov_b32_e32 v62, v64
	v_mov_b32_e32 v63, v26
	v_mov_b32_e32 v26, v65
	s_waitcnt lgkmcnt(9)
	v_mov_b32_e32 v64, v70
	s_waitcnt lgkmcnt(7)
	v_mov_b32_e32 v65, v28
	v_mov_b32_e32 v28, v71
	v_mov_b32_e32 v70, v72
	v_mov_b32_e32 v71, v30
	v_mov_b32_e32 v30, v73
	s_waitcnt lgkmcnt(5)
	v_mov_b32_e32 v72, v78
	s_waitcnt lgkmcnt(3)
	v_mov_b32_e32 v73, v86
	v_mov_b32_e32 v86, v79
	v_mov_b32_e32 v78, v80
	v_mov_b32_e32 v79, v88
	v_mov_b32_e32 v88, v81
	v_mov_b32_e32 v80, v0
	v_mov_b32_e32 v81, v12
	v_mov_b32_e32 v12, v1
	v_mov_b32_e32 v0, v2
	v_mov_b32_e32 v1, v14
	v_mov_b32_e32 v14, v3
	v_mov_b32_e32 v2, v66
	v_mov_b32_e32 v3, v16
	v_mov_b32_e32 v16, v67
	v_mov_b32_e32 v66, v68
	v_mov_b32_e32 v67, v18
	v_mov_b32_e32 v18, v69
	v_mov_b32_e32 v68, v74
	v_mov_b32_e32 v69, v20
	v_mov_b32_e32 v20, v75
	v_mov_b32_e32 v74, v76
	v_mov_b32_e32 v75, v22
	v_mov_b32_e32 v22, v77
	v_mov_b32_e32 v76, v82
	s_waitcnt lgkmcnt(2)
	v_mov_b32_e32 v77, v32
	v_mov_b32_e32 v32, v83
	s_add_u32 s10, s10, 0x30000
	v_mov_b32_e32 v82, v84
	v_mov_b32_e32 v83, v34
	s_addc_u32 s11, s11, 0
	v_mov_b32_e32 v34, v85
	v_add_u32_e32 v60, 32, v60
	s_cmp_eq_u32 s10, 0x300000
	s_nop 0
	v_pk_fma_f32 v[48:49], v[112:113], v[114:115], v[48:49] op_sel_hi:[0,1,1]
	v_pk_fma_f32 v[10:11], v[112:113], v[10:11], v[50:51] op_sel_hi:[0,1,1]
	v_pk_fma_f32 v[50:51], v[112:113], v[64:65], v[52:53] op_sel_hi:[0,1,1]
	v_pk_fma_f32 v[52:53], v[112:113], v[72:73], v[54:55] op_sel_hi:[0,1,1]
	s_waitcnt lgkmcnt(1)
	v_fmac_f32_e32 v61, v112, v90
	s_nop 0
	v_pk_fma_f32 v[4:5], v[100:101], v[4:5], v[48:49] op_sel_hi:[0,1,1]
	v_pk_fma_f32 v[10:11], v[100:101], v[24:25], v[10:11] op_sel_hi:[0,1,1]
	v_pk_fma_f32 v[24:25], v[100:101], v[28:29], v[50:51] op_sel_hi:[0,1,1]
	v_pk_fma_f32 v[28:29], v[100:101], v[86:87], v[52:53] op_sel_hi:[0,1,1]
	v_fmac_f32_e32 v61, v100, v91
	s_nop 0
	v_pk_fma_f32 v[4:5], v[102:103], v[8:9], v[4:5] op_sel_hi:[0,1,1]
	v_pk_fma_f32 v[8:9], v[102:103], v[62:63], v[10:11] op_sel_hi:[0,1,1]
	v_pk_fma_f32 v[10:11], v[102:103], v[70:71], v[24:25] op_sel_hi:[0,1,1]
	v_pk_fma_f32 v[24:25], v[102:103], v[78:79], v[28:29] op_sel_hi:[0,1,1]
	v_fmac_f32_e32 v61, v102, v92
	s_nop 0
	v_pk_fma_f32 v[4:5], v[104:105], v[6:7], v[4:5] op_sel_hi:[0,1,1]
	v_pk_fma_f32 v[6:7], v[104:105], v[26:27], v[8:9] op_sel_hi:[0,1,1]
	v_pk_fma_f32 v[8:9], v[104:105], v[30:31], v[10:11] op_sel_hi:[0,1,1]
	v_pk_fma_f32 v[10:11], v[104:105], v[88:89], v[24:25] op_sel_hi:[0,1,1]
	v_fmac_f32_e32 v61, v104, v93
	s_nop 0
	v_pk_fma_f32 v[4:5], v[106:107], v[80:81], v[4:5] op_sel_hi:[0,1,1]
	v_pk_fma_f32 v[2:3], v[106:107], v[2:3], v[6:7] op_sel_hi:[0,1,1]
	v_pk_fma_f32 v[6:7], v[106:107], v[68:69], v[8:9] op_sel_hi:[0,1,1]
	v_pk_fma_f32 v[8:9], v[106:107], v[76:77], v[10:11] op_sel_hi:[0,1,1]
	s_waitcnt lgkmcnt(0)
	v_fmac_f32_e32 v61, v106, v94
	s_nop 0
	v_pk_fma_f32 v[4:5], v[108:109], v[12:13], v[4:5] op_sel_hi:[0,1,1]
	v_pk_fma_f32 v[2:3], v[108:109], v[16:17], v[2:3] op_sel_hi:[0,1,1]
	v_pk_fma_f32 v[6:7], v[108:109], v[20:21], v[6:7] op_sel_hi:[0,1,1]
	v_pk_fma_f32 v[8:9], v[108:109], v[32:33], v[8:9] op_sel_hi:[0,1,1]
	v_fmac_f32_e32 v61, v108, v95
	s_nop 0
	v_pk_fma_f32 v[0:1], v[110:111], v[0:1], v[4:5] op_sel_hi:[0,1,1]
	v_pk_fma_f32 v[2:3], v[110:111], v[66:67], v[2:3] op_sel_hi:[0,1,1]
	v_pk_fma_f32 v[4:5], v[110:111], v[74:75], v[6:7] op_sel_hi:[0,1,1]
	v_pk_fma_f32 v[6:7], v[110:111], v[82:83], v[8:9] op_sel_hi:[0,1,1]
	v_fmac_f32_e32 v61, v110, v96
	s_nop 0
	v_pk_fma_f32 v[48:49], v[98:99], v[14:15], v[0:1] op_sel_hi:[0,1,1]
	v_pk_fma_f32 v[50:51], v[98:99], v[18:19], v[2:3] op_sel_hi:[0,1,1]
	v_pk_fma_f32 v[52:53], v[98:99], v[22:23], v[4:5] op_sel_hi:[0,1,1]
	v_pk_fma_f32 v[54:55], v[98:99], v[34:35], v[6:7] op_sel_hi:[0,1,1]
	v_fmac_f32_e32 v61, v98, v97
	s_cbranch_scc0 .LBB0_81
	ds_write2st64_b32 v59, v48, v49 offset0:160 offset1:161
	ds_write2st64_b32 v59, v50, v51 offset0:162 offset1:163
	ds_write2st64_b32 v59, v52, v53 offset0:164 offset1:165
	ds_write2st64_b32 v59, v54, v55 offset0:166 offset1:167
	ds_write_b32 v59, v61 offset:43008
	s_waitcnt lgkmcnt(0)
	s_barrier
	s_and_saveexec_b64 s[10:11], vcc
	s_cbranch_execz .LBB0_79
	s_mul_i32 s2, s6, 0x1800
	s_add_i32 s2, s2, s8
	v_or_b32_e32 v0, s2, v36
	s_mul_hi_i32 s7, s6, 0x36000
	s_mul_i32 s6, s6, 0x36000
	s_lshl_b64 s[2:3], s[8:9], 2
	s_add_u32 s2, s6, s2
	v_ashrrev_i32_e32 v1, 31, v0
	s_addc_u32 s3, s7, s3
	v_lshl_add_u64 v[0:1], v[0:1], 2, s[62:63]
	v_lshl_add_u64 v[2:3], v[40:41], 0, s[2:3]
	s_mov_b64 s[6:7], 0
	v_mov_b32_e32 v4, v58
	v_mov_b32_e32 v5, v57
